# P2 static prio waves 4-7
# speedup vs baseline: 1.0032x; 1.0005x over previous
.LBB0_207:
	s_or_b64 exec, exec, s[0:1]
	s_ashr_i32 s29, s28, 31
	v_writelane_b32 v255, s30, 11
	s_lshl_b32 s0, s30, 2
	v_writelane_b32 v255, s28, 12
	s_lshl_b32 s38, s28, 11
	s_cmp_lt_u32 s4, 64
	v_mov_b32_e32 v0, s0
	v_writelane_b32 v255, s29, 13
	s_cselect_b64 s[0:1], -1, 0
	v_writelane_b32 v255, s0, 14
	s_waitcnt lgkmcnt(0)
	s_barrier
	s_mov_b32 s40, 0
	v_writelane_b32 v255, s1, 15
	s_and_b32 s0, s4, 0x3fffffc0
	s_lshl_b32 s0, s0, 2
	s_add_i32 s0, s0, 0
	s_add_i32 s0, s0, 0x1f800
	s_cmp_eq_u32 s8, 7
	v_writelane_b32 v255, s0, 16
	s_cselect_b64 s[0:1], -1, 0
	v_writelane_b32 v255, s0, 17
	s_mov_b64 s[54:55], 0
	s_nop 0
	v_writelane_b32 v255, s1, 18
	v_readlane_b32 s1, v254, 45
	v_readlane_b32 s0, v255, 9
	s_lshl_b32 s0, s0, 1
	s_add_u32 s44, s1, s0
	v_readlane_b32 s0, v254, 46
	s_addc_u32 s45, s0, 0
	s_cmp_lt_i32 s8, 0
	s_cselect_b64 s[80:81], -1, 0
	s_cmp_gt_i32 s8, 0
	s_cselect_b64 s[82:83], -1, 0
	s_cmp_gt_i32 s8, 1
	s_cselect_b64 s[84:85], -1, 0
	s_cmp_gt_i32 s8, 2
	s_cselect_b64 s[86:87], -1, 0
	s_cmp_gt_i32 s8, 3
	s_cselect_b64 s[88:89], -1, 0
	s_cmp_gt_i32 s8, 4
	s_cselect_b64 s[90:91], -1, 0
	s_cmp_gt_i32 s8, 5
	s_cselect_b64 s[92:93], -1, 0
	s_cmp_gt_i32 s8, 6
	s_cselect_b64 s[94:95], -1, 0
	s_cmp_lt_i32 s8, 8
	s_cselect_b64 s[0:1], -1, 0
	s_and_b32 s79, s34, 0x70
	s_cmp_lt_i32 s8, 7
	v_writelane_b32 v255, s0, 19
	s_cselect_b64 s[98:99], -1, 0
	s_add_i32 s71, s34, 16
	v_writelane_b32 v255, s1, 20
	s_and_b32 s77, s71, 0x70
	s_add_i32 s0, s8, 2
	s_cmp_lt_i32 s8, 6
	s_cselect_b64 s[4:5], -1, 0
	s_lshl_b32 s74, s0, 4
	s_and_b32 s36, s74, 0x70
	s_cmp_lt_i32 s8, 5
	s_cselect_b64 s[26:27], -1, 0
	s_add_i32 s37, s34, 48
	s_and_b32 s72, s37, 0x70
	s_add_i32 s1, s8, 4
	s_cmp_lt_i32 s8, 4
	s_cselect_b64 s[24:25], -1, 0
	s_lshl_b32 s42, s1, 4
	s_and_b32 s43, s42, 0x70
	s_cmp_lt_i32 s8, 3
	s_cselect_b64 s[28:29], -1, 0
	s_add_i32 s46, s34, 0x50
	s_and_b32 s47, s46, 0x70
	s_add_i32 s9, s8, 6
	s_cmp_lt_i32 s8, 2
	s_cselect_b64 s[2:3], -1, 0
	s_lshl_b32 s48, s9, 4
	s_and_b32 s49, s48, 0x70
	s_cmp_lt_i32 s8, 1
	s_cselect_b64 s[30:31], -1, 0
	s_min_i32 s0, s0, 14
	s_lshl_b32 s0, s0, 4
	s_add_i32 s0, s0, 16
	s_and_b32 s51, s0, 0x70
	s_min_i32 s0, s1, 14
	s_lshl_b32 s0, s0, 4
	s_add_i32 s0, s0, 16
	s_and_b32 s33, s0, 0x70
	s_min_i32 s0, s9, 14
	s_lshl_b32 s0, s0, 4
	s_min_i32 s10, s8, 14
	s_add_i32 s0, s0, 16
	s_lshl_b32 s10, s10, 4
	s_and_b32 s35, s0, 0x70
	s_add_i32 s0, s8, 8
	s_add_i32 s10, s10, 16
	s_lshl_b32 s67, s0, 4
	s_add_i32 s62, s34, 0x70
	s_and_b32 s50, s10, 0x70
	s_min_i32 s0, s0, 14
	s_and_b32 s76, s62, 0x70
	s_and_b32 s73, s67, 0x70
	s_cmp_lt_i32 s8, -1
	v_readlane_b32 s8, v254, 23
	v_readlane_b32 s9, v254, 24
	v_readlane_b32 s10, v254, 25
	v_readlane_b32 s11, v254, 26
	v_readlane_b32 s12, v254, 27
	v_readlane_b32 s13, v254, 28
	v_readlane_b32 s14, v254, 29
	global_load_dword v0, v0, s[8:9]
	v_readlane_b32 s15, v254, 30
	v_readlane_b32 s16, v254, 31
	v_readlane_b32 s17, v254, 32
	v_readlane_b32 s18, v254, 33
	v_readlane_b32 s19, v254, 34
	v_readlane_b32 s20, v254, 35
	v_readlane_b32 s21, v254, 36
	v_readlane_b32 s22, v254, 37
	v_readlane_b32 s23, v254, 38
	v_writelane_b32 v255, s38, 21
	v_readlane_b32 s8, v254, 53
	s_cselect_b64 s[52:53], -1, 0
	s_lshl_b32 s0, s0, 4
	v_readlane_b32 s16, v254, 61
	v_readlane_b32 s17, v254, 62
	v_readlane_b32 s18, v254, 63
	v_readlane_b32 s19, v255, 0
	v_readlane_b32 s20, v255, 1
	v_readlane_b32 s21, v255, 2
	s_add_i32 s0, s0, 16
	v_readlane_b32 s22, v255, 3
	v_readlane_b32 s23, v255, 4
	s_mov_b64 s[16:17], s[20:21]
	s_and_b32 s75, s0, 0x70
	s_add_i32 s38, s38, s34
	s_mov_b64 s[18:19], s[22:23]
	s_add_u32 s39, s18, s7
	s_addc_u32 s78, s19, s6
	v_readlane_b32 s9, v254, 54
	v_readlane_b32 s10, v254, 55
	v_readlane_b32 s11, v254, 56
	v_readlane_b32 s12, v254, 57
	v_readlane_b32 s13, v254, 58
	v_readlane_b32 s14, v254, 59
	v_readlane_b32 s15, v254, 60
	s_waitcnt vmcnt(0)
	v_mul_f32_e32 v53, 0x3fb8aa3b, v0
	s_cmp_ge_u32 s34, 64
	s_cbranch_scc0 .Lp2prio_skip
	s_setprio 1
.Lp2prio_skip:
	s_branch .LBB0_209

.LBB0_281:
	s_setprio 0
	s_nop 0
	v_cmp_gt_i32_e32 vcc, 64, v52
	s_and_saveexec_b64 s[0:1], vcc
	v_readlane_b32 s4, v254, 53
	v_readlane_b32 s8, v254, 57
	v_readlane_b32 s9, v254, 58
	v_readlane_b32 s18, v255, 3
	v_readlane_b32 s19, v255, 4
	v_readlane_b32 s10, v254, 59
	v_readlane_b32 s11, v254, 60
	v_readlane_b32 s14, v254, 63
	v_readlane_b32 s15, v255, 0
	v_readlane_b32 s16, v255, 1
	v_readlane_b32 s17, v255, 2
	s_mov_b64 s[82:83], s[18:19]
	v_readlane_b32 s8, v255, 12
	s_mov_b64 s[80:81], s[16:17]
	s_mov_b64 s[74:75], s[10:11]
	s_mov_b64 s[78:79], s[14:15]
	v_readlane_b32 s9, v255, 13
	v_readlane_b32 s5, v254, 54
	v_readlane_b32 s6, v254, 55
	v_readlane_b32 s7, v254, 56
	v_readlane_b32 s12, v254, 61
	v_readlane_b32 s13, v254, 62
	s_cbranch_execz .LBB0_283
	s_lshl_b64 s[2:3], s[8:9], 12
	v_lshl_add_u32 v0, v52, 2, 0
	s_add_u32 s2, s80, s2
	v_readlane_b32 s4, v255, 9
	v_add_u32_e32 v2, 0x20800, v0
	s_addc_u32 s3, s81, s3
	s_lshl_b32 s4, s4, 2
	s_add_u32 s2, s2, s4
	ds_read_b32 v2, v2
	s_addc_u32 s3, s3, 0
	v_ashrrev_i32_e32 v53, 31, v52
	v_lshl_add_u64 v[0:1], v[52:53], 2, s[2:3]
	v_add_co_u32_e32 v0, vcc, 0x84b0000, v0
	s_nop 1
	v_addc_co_u32_e32 v1, vcc, 0, v1, vcc
	s_waitcnt lgkmcnt(0)
	global_store_dword v[0:1], v2, off
